# F3 norm loop: gain vectors register-resident as in X5
# baseline (speedup 1.0000x reference)
; template <bool XOUT_BF, int NR>
; DI void norm_rows(const bf16_t* xin, const bf16_t* Rb, const float* gpost, void* xout, const float* gpre, bf16_t* xnb, size_t row0, size_t rstride, int lane) {
;     f32x4 v[NR][4], r[NR][4];
; #pragma unroll
;     for (int q = 0; q < NR; ++q)
; #pragma unroll
;         for (int j = 0; j < 4; ++j) { const size_t off = (row0 + q * rstride) * D + 4 * lane + 256 * j;
; __global__ void __launch_bounds__(512, 2) mega(Args args) {
;     ...
;             const bool more = l + 1 < DEPTH;
;             if (more) { for (int m = gw; m < TT; m += 4 * NGW) norm_rows<true, 4>(XB, R, in.g_ff_post + l * D, XB, in.g_mix_pre + (l + 1) * D, XN, (size_t)m, (size_t)NGW, lane); }
.LBB0_1582:
	v_readlane_b32 s4, v255, 1
	v_readlane_b32 s5, v255, 2
	s_cmp_ge_i32 s26, s4
	s_cselect_b64 s[4:5], -1, 0
	s_and_b64 s[2:3], s[4:5], s[2:3]
	s_andn2_b64 vcc, exec, s[2:3]
	s_cbranch_vccnz .LBB0_1671
	s_mov_b64 s[4:5], s[84:85]
	s_load_dwordx2 s[46:47], s[4:5], 0x30
	s_load_dwordx8 s[8:15], s[4:5], 0x40
	s_load_dwordx2 s[6:7], s[4:5], 0x60
	s_load_dwordx4 s[28:31], s[4:5], 0x88
	s_load_dwordx2 s[40:41], s[4:5], 0xc0
	s_load_dwordx4 s[24:27], s[4:5], 0xb0
	s_load_dwordx2 s[34:35], s[4:5], 0xf0
	s_load_dwordx8 s[16:23], s[4:5], 0xd0
	s_mov_b32 s33, s81
	v_readlane_b32 s58, v255, 0
	s_mov_b32 s2, s83
	v_readlane_b32 s59, v255, 3
	s_lshl_b32 s2, s58, 3
	s_add_i32 s36, s2, s59
	s_lshl_b32 s38, s33, 3
	s_add_i32 s44, s79, 1
	s_cmp_lg_u32 s79, 3
	s_cselect_b64 s[48:49], -1, 0
	s_cmp_lt_i32 s36, 0x8000
	s_cselect_b64 s[2:3], -1, 0
	v_lshl_add_u32 v48, s59, 6, v249
	v_cndmask_b32_e64 v0, 0, 1, s[2:3]
	s_cmp_eq_u32 s79, 3
	v_and_b32_e32 v110, 63, v48
	s_mov_b64 s[50:51], -1
	v_cmp_ne_u32_e64 s[2:3], 1, v0
	s_cbranch_scc1 .LBB0_1590
	s_and_b64 vcc, exec, s[2:3]
	s_cbranch_vccnz .LBB0_1589
	v_readlane_b32 s50, v255, 15
	v_readlane_b32 s51, v255, 16
	s_lshl_b64 s[50:51], s[50:51], 2
	s_load_dwordx2 s[4:5], s[4:5], 0x20
	s_waitcnt lgkmcnt(0)
	s_add_u32 s50, s16, s50
	s_addc_u32 s51, s17, s51
	s_ashr_i32 s39, s38, 31
	s_cmp_lg_u64 s[22:23], 0
	s_cselect_b64 s[52:53], -1, 0
	s_lshl_b32 s54, s44, 10
	s_mov_b32 s55, s45
	s_lshl_b64 s[54:55], s[54:55], 2
	s_add_u32 s4, s4, s54
	s_addc_u32 s5, s5, s55
	s_lshl_b32 s54, s33, 5
	v_lshlrev_b32_e32 v176, 4, v110
	s_ashr_i32 s37, s36, 31
	s_ashr_i32 s55, s54, 31
	v_lshl_add_u64 v[6:7], s[4:5], 0, v[176:177]
	s_lshl_b64 s[4:5], s[36:37], 11
	v_lshlrev_b32_e32 v0, 3, v48
	s_lshl_b64 s[56:57], s[54:55], 11
	s_lshl_b64 s[60:61], s[38:39], 12
	v_and_b32_e32 v2, 0x1f8, v0
	s_add_u32 s42, s60, s4
	v_or_b32_e32 v0, s4, v2
	v_mov_b32_e32 v1, s5
	s_addc_u32 s55, s61, s5
	v_lshl_add_u64 v[8:9], s[34:35], 0, v[0:1]
	v_lshl_add_u64 v[10:11], s[22:23], 0, v[0:1]
	v_mov_b32_e32 v1, s55
	s_mul_i32 s55, s38, 0x1800
	v_or_b32_e32 v0, s42, v2
	s_mul_hi_i32 s42, s38, 0x1800
	s_add_u32 s4, s55, s4
	s_addc_u32 s5, s42, s5
	v_lshl_add_u64 v[12:13], s[34:35], 0, v[0:1]
	v_lshl_add_u64 v[14:15], s[22:23], 0, v[0:1]
	v_or_b32_e32 v0, s4, v2
	s_add_u32 s4, s38, s36
	v_mov_b32_e32 v1, s5
	s_addc_u32 s5, s39, s37
	s_lshl_b64 s[4:5], s[4:5], 11
	v_or_b32_e32 v2, s4, v2
	v_mov_b32_e32 v3, s5
	v_lshl_add_u64 v[4:5], s[50:51], 0, v[176:177]
	global_load_dwordx4 v[140:143], v[4:5], off
	global_load_dwordx4 v[144:147], v[4:5], off offset:1024
	global_load_dwordx4 v[148:151], v[4:5], off offset:2048
	global_load_dwordx4 v[152:155], v[4:5], off offset:3072
	global_load_dwordx4 v[156:159], v[6:7], off
	global_load_dwordx4 v[160:163], v[6:7], off offset:1024
	global_load_dwordx4 v[164:167], v[6:7], off offset:2048
	global_load_dwordx4 v[168:171], v[6:7], off offset:3072
	s_mov_b64 s[50:51], 0
	v_lshl_add_u64 v[16:17], s[34:35], 0, v[0:1]
	v_lshl_add_u64 v[18:19], s[34:35], 0, v[2:3]
	v_lshl_add_u64 v[20:21], s[22:23], 0, v[0:1]
	v_lshl_add_u64 v[22:23], s[22:23], 0, v[2:3]
	s_mov_b32 s37, s36
	s_branch .LBB0_1587

; DI float bflo(unsigned w) { return __uint_as_float(w << 16); }
; DI float bfhi(unsigned w) { return __uint_as_float(w & 0xffff0000u); }
; template <bool XOUT_BF, int NR>
; DI void norm_rows(const bf16_t* xin, const bf16_t* Rb, const float* gpost, void* xout, const float* gpre, bf16_t* xnb, size_t row0, size_t rstride, int lane) {
;     f32x4 v[NR][4], r[NR][4];
; #pragma unroll
;     for (int q = 0; q < NR; ++q)
; #pragma unroll
;         for (int j = 0; j < 4; ++j) { const size_t off = (row0 + q * rstride) * D + 4 * lane + 256 * j;
;             const u32x2 w = __builtin_nontemporal_load((const u32x2*)(xin + off)); v[q][j] = (f32x4){bflo(w.x), bfhi(w.x), bflo(w.y), bfhi(w.y)};
;             const u32x2 w2 = __builtin_nontemporal_load((const u32x2*)(Rb + off)); r[q][j] = (f32x4){bflo(w2.x), bfhi(w2.x), bflo(w2.y), bfhi(w2.y)}; }
;     float ss[NR], s2[NR];
; #pragma unroll
;     for (int q = 0; q < NR; ++q) { ss[q] = 0.f; s2[q] = 0.f;
; #pragma unroll
;         for (int j = 0; j < 4; ++j) ss[q] += (r[q][j][0] * r[q][j][0] + r[q][j][1] * r[q][j][1]) + (r[q][j][2] * r[q][j][2] + r[q][j][3] * r[q][j][3]); }
; #pragma unroll
;     for (int o = 1; o < 64; o <<= 1)
; #pragma unroll
;         for (int q = 0; q < NR; ++q) ss[q] += __shfl_xor(ss[q], o);
.LBB0_1587:
	s_waitcnt vmcnt(16)
	v_lshl_add_u64 v[28:29], v[8:9], 0, s[50:51]
	v_add_co_u32_e32 v24, vcc, 0x3d00000, v28
	s_mov_b64 s[4:5], vcc
	v_add_co_u32_e32 v0, vcc, 0x7d00000, v28
	v_lshl_add_u64 v[26:27], v[18:19], 0, s[50:51]
	s_nop 0
	v_addc_co_u32_e32 v1, vcc, 0, v29, vcc
	global_load_dwordx2 v[36:37], v[0:1], off offset:1536 nt
	global_load_dwordx2 v[34:35], v[0:1], off nt
	global_load_dwordx2 v[32:33], v[0:1], off offset:512 nt
	global_load_dwordx2 v[30:31], v[0:1], off offset:1024 nt
	s_mov_b32 s39, 0x3d00000
	v_add_co_u32_e32 v64, vcc, s39, v26
	s_mov_b32 s42, 0x7d00000
	s_nop 0
	v_addc_co_u32_e32 v65, vcc, 0, v27, vcc
	v_add_co_u32_e32 v46, vcc, s42, v26
	v_lshl_add_u64 v[38:39], v[12:13], 0, s[50:51]
	s_nop 0
	v_addc_co_u32_e32 v47, vcc, 0, v27, vcc
	v_add_co_u32_e32 v40, vcc, s39, v38
	v_lshl_add_u64 v[42:43], v[16:17], 0, s[50:51]
	s_nop 0
	v_addc_co_u32_e32 v41, vcc, 0, v39, vcc
	v_add_co_u32_e32 v50, vcc, s42, v38
	s_nop 0
	v_addc_co_u32_e32 v51, vcc, 0, v39, vcc
	v_add_co_u32_e32 v26, vcc, s39, v42
	s_waitcnt vmcnt(0)
	v_mov_b32_e32 v0, v140
	v_mov_b32_e32 v1, v141
	v_mov_b32_e32 v2, v142
	v_mov_b32_e32 v3, v143
	v_lshlrev_b32_e32 v83, 16, v36
	v_addc_co_u32_e32 v27, vcc, 0, v43, vcc
	v_add_co_u32_e32 v58, vcc, s42, v42
	v_and_b32_e32 v101, 0xffff0000, v34
	s_nop 0
	v_addc_co_u32_e32 v59, vcc, 0, v43, vcc
	v_addc_co_u32_e64 v25, vcc, 0, v29, s[4:5]
	global_load_dwordx2 v[108:109], v[24:25], off nt
	global_load_dwordx2 v[76:77], v[64:65], off nt
	global_load_dwordx2 v[38:39], v[64:65], off offset:512 nt
	global_load_dwordx2 v[44:45], v[64:65], off offset:1024 nt
	global_load_dwordx2 v[54:55], v[64:65], off offset:1536 nt
	v_and_b32_e32 v103, 0xffff0000, v35
	v_lshlrev_b32_e32 v100, 16, v34
	v_lshlrev_b32_e32 v102, 16, v35
	v_lshlrev_b32_e32 v96, 16, v32
	v_and_b32_e32 v95, 0xffff0000, v33
	v_and_b32_e32 v94, 0xffff0000, v32
	v_mul_f32_e32 v28, v103, v103
	v_mul_f32_e32 v32, v101, v101
	v_mov_b32_e32 v29, v83
	v_lshlrev_b32_e32 v97, 16, v33
	v_lshlrev_b32_e32 v34, 16, v30
	v_and_b32_e32 v35, 0xffff0000, v30
	v_lshlrev_b32_e32 v90, 16, v31
	v_and_b32_e32 v91, 0xffff0000, v31
	v_pk_mul_f32 v[30:31], v[94:95], v[94:95]
	v_pk_fma_f32 v[52:53], v[102:103], v[102:103], v[28:29] op_sel_hi:[1,1,0]
	v_pk_fma_f32 v[32:33], v[100:101], v[100:101], v[32:33] op_sel_hi:[1,1,0]
	v_and_b32_e32 v81, 0xffff0000, v36
	v_lshlrev_b32_e32 v78, 16, v37
	v_and_b32_e32 v79, 0xffff0000, v37
	v_mul_f32_e32 v36, v35, v35
	v_mul_f32_e32 v42, v91, v91
	v_pk_fma_f32 v[30:31], v[96:97], v[96:97], v[30:31]
	v_mov_b32_e32 v82, v32
	v_mov_b32_e32 v28, v52
	v_mul_f32_e32 v49, v81, v81
	v_mul_f32_e32 v56, v78, v78
	v_mul_f32_e32 v57, v79, v79
	v_pk_fma_f32 v[36:37], v[34:35], v[34:35], v[36:37] op_sel_hi:[1,1,0]
	v_pk_fma_f32 v[42:43], v[90:91], v[90:91], v[42:43] op_sel_hi:[1,1,0]
	v_pk_add_f32 v[32:33], v[32:33], v[52:53]
	v_pk_add_f32 v[30:31], v[30:31], v[30:31] op_sel:[0,1] op_sel_hi:[1,0]
	v_pk_mul_f32 v[28:29], v[82:83], v[28:29]
	v_mov_b32_e32 v37, v56
	v_mov_b32_e32 v43, v57
	v_mov_b32_e32 v31, v49
	v_mov_b32_e32 v33, v29
	v_pk_add_f32 v[36:37], v[36:37], v[42:43]
	v_pk_add_f32 v[28:29], v[32:33], v[30:31]
	global_load_dwordx2 v[88:89], v[46:47], off nt
	global_load_dwordx2 v[86:87], v[46:47], off offset:512 nt
	global_load_dwordx2 v[84:85], v[46:47], off offset:1024 nt
	global_load_dwordx2 v[92:93], v[46:47], off offset:1536 nt
	v_pk_add_f32 v[28:29], v[28:29], v[36:37]
	global_load_dwordx2 v[66:67], v[40:41], off nt
	global_load_dwordx2 v[62:63], v[40:41], off offset:512 nt
	global_load_dwordx2 v[60:61], v[40:41], off offset:1024 nt
	global_load_dwordx2 v[56:57], v[40:41], off offset:1536 nt
	v_add_f32_e32 v28, v28, v29
	ds_bpermute_b32 v29, v206, v28
	global_load_dwordx2 v[72:73], v[50:51], off nt
	global_load_dwordx2 v[70:71], v[50:51], off offset:512 nt
	global_load_dwordx2 v[68:69], v[50:51], off offset:1024 nt
	global_load_dwordx2 v[74:75], v[50:51], off offset:1536 nt
	v_mov_b32_e32 v80, v83
	s_andn2_b64 vcc, exec, s[52:53]
	s_waitcnt lgkmcnt(0)
	v_add_f32_e32 v28, v28, v29
	ds_bpermute_b32 v29, v207, v28
	s_waitcnt lgkmcnt(0)
	v_add_f32_e32 v28, v28, v29
	ds_bpermute_b32 v29, v208, v28
	s_waitcnt lgkmcnt(0)
	v_add_f32_e32 v32, v28, v29
	ds_bpermute_b32 v33, v209, v32
	global_load_dwordx2 v[42:43], v[26:27], off nt
	global_load_dwordx2 v[36:37], v[26:27], off offset:512 nt
	global_load_dwordx2 v[30:31], v[26:27], off offset:1024 nt
	global_load_dwordx2 v[28:29], v[26:27], off offset:1536 nt
	global_load_dwordx2 v[52:53], v[58:59], off nt
	global_load_dwordx2 v[50:51], v[58:59], off offset:512 nt
	global_load_dwordx2 v[46:47], v[58:59], off offset:1024 nt
	s_nop 0
	global_load_dwordx2 v[58:59], v[58:59], off offset:1536 nt
	s_nop 0
	global_load_dwordx2 v[106:107], v[24:25], off offset:512 nt
	global_load_dwordx2 v[104:105], v[24:25], off offset:1024 nt
	global_load_dwordx2 v[98:99], v[24:25], off offset:1536 nt
	s_waitcnt lgkmcnt(0)
	v_add_f32_e32 v32, v32, v33
	ds_bpermute_b32 v33, v210, v32
	s_waitcnt lgkmcnt(0)
	v_add_f32_e32 v33, v32, v33
	ds_bpermute_b32 v49, v211, v33
	s_waitcnt vmcnt(0)
	v_lshlrev_b32_e32 v32, 16, v108
	s_waitcnt lgkmcnt(0)
; DI unsigned cvt_pk_bf16(float lo, float hi) { const f32x2 v = {lo, hi}; return __builtin_bit_cast(unsigned, __builtin_convertvector(v, bf16x2_t)); }
; DI float bflo(unsigned w) { return __uint_as_float(w << 16); }
; DI float bfhi(unsigned w) { return __uint_as_float(w & 0xffff0000u); }
; template <bool XOUT_BF, int NR>
; DI void norm_rows(const bf16_t* xin, const bf16_t* Rb, const float* gpost, void* xout, const float* gpre, bf16_t* xnb, size_t row0, size_t rstride, int lane) {
;     ...
;     for (int q = 0; q < NR; ++q) { const float rinv = __builtin_amdgcn_rsqf(ss[q] * (1.f / 1024.f) + EPS);
; #pragma unroll
;         for (int j = 0; j < 4; ++j) { const size_t off = (row0 + q * rstride) * D + 4 * lane + 256 * j;
;             const f32x4 g = *(const f32x4*)(gpost + 4 * lane + 256 * j); v[q][j] += r[q][j] * rinv * g;
;             if (XOUT_BF) { u32x2 w; w.x = cvt_pk_bf16(v[q][j][0], v[q][j][1]); w.y = cvt_pk_bf16(v[q][j][2], v[q][j][3]); __builtin_nontemporal_store(w, (u32x2*)((bf16_t*)xout + off));
;                            v[q][j] = (f32x4){bflo(w.x), bfhi(w.x), bflo(w.y), bfhi(w.y)}; }
;             else *(f32x4*)((float*)xout + off) = v[q][j];
;             s2[q] += (v[q][j][0] * v[q][j][0] + v[q][j][1] * v[q][j][1]) + (v[q][j][2] * v[q][j][2] + v[q][j][3] * v[q][j][3]); } }
;     if (xnb) {
; #pragma unroll
;         for (int o = 1; o < 64; o <<= 1)
; #pragma unroll
;             for (int q = 0; q < NR; ++q) s2[q] += __shfl_xor(s2[q], o);
	v_add_f32_e32 v33, v33, v49
	v_fmamk_f32 v33, v33, 0x3a800000, v217
	v_rsq_f32_e32 v82, v33
	v_and_b32_e32 v33, 0xffff0000, v108
	v_lshlrev_b32_e32 v108, 16, v109
	v_and_b32_e32 v109, 0xffff0000, v109
	v_pk_mul_f32 v[100:101], v[82:83], v[100:101] op_sel_hi:[0,1]
	v_pk_mul_f32 v[102:103], v[82:83], v[102:103] op_sel_hi:[0,1]
	v_pk_fma_f32 v[2:3], v[2:3], v[102:103], v[108:109]
	v_pk_fma_f32 v[0:1], v[0:1], v[100:101], v[32:33]
	v_cvt_pk_bf16_f32 v33, v2, v3
	v_cvt_pk_bf16_f32 v32, v0, v1
	global_store_dwordx2 v[24:25], v[32:33], off nt
	v_pk_mul_f32 v[34:35], v[82:83], v[34:35] op_sel_hi:[0,1]
	v_pk_mul_f32 v[90:91], v[82:83], v[90:91] op_sel_hi:[0,1]
	v_pk_mul_f32 v[80:81], v[82:83], v[80:81] op_sel_hi:[0,1]
	v_pk_mul_f32 v[78:79], v[82:83], v[78:79] op_sel_hi:[0,1]
	s_nop 0
	v_mov_b32_e32 v0, v144
	v_mov_b32_e32 v1, v145
	v_mov_b32_e32 v2, v146
	v_mov_b32_e32 v3, v147
	v_lshlrev_b32_e32 v100, 16, v106
	v_and_b32_e32 v101, 0xffff0000, v106
	v_lshlrev_b32_e32 v102, 16, v107
	v_and_b32_e32 v103, 0xffff0000, v107
	v_mov_b32_e32 v106, v96
	v_mov_b32_e32 v107, v94
	v_mov_b32_e32 v94, v97
	v_pk_mul_f32 v[96:97], v[82:83], v[106:107] op_sel_hi:[0,1]
	v_pk_mul_f32 v[94:95], v[82:83], v[94:95] op_sel_hi:[0,1]
	v_and_b32_e32 v83, 0xffff0000, v85
	v_lshlrev_b32_e32 v82, 16, v85
	s_nop 0
	v_pk_fma_f32 v[2:3], v[2:3], v[94:95], v[102:103]
	v_pk_fma_f32 v[0:1], v[0:1], v[96:97], v[100:101]
	v_lshlrev_b32_e32 v100, 16, v105
	v_cvt_pk_bf16_f32 v0, v0, v1
	v_cvt_pk_bf16_f32 v1, v2, v3
	global_store_dwordx2 v[24:25], v[0:1], off offset:512 nt
	v_lshlrev_b32_e32 v2, 16, v104
	v_and_b32_e32 v3, 0xffff0000, v104
	v_and_b32_e32 v101, 0xffff0000, v105
	s_nop 0
	v_mov_b32_e32 v94, v148
	v_mov_b32_e32 v95, v149
	v_mov_b32_e32 v96, v150
	v_mov_b32_e32 v97, v151
	v_pk_fma_f32 v[90:91], v[96:97], v[90:91], v[100:101]
	v_pk_fma_f32 v[2:3], v[94:95], v[34:35], v[2:3]
	v_lshlrev_b32_e32 v34, 16, v98
	v_cvt_pk_bf16_f32 v2, v2, v3
	v_cvt_pk_bf16_f32 v3, v90, v91
	global_store_dwordx2 v[24:25], v[2:3], off offset:1024 nt
	v_and_b32_e32 v35, 0xffff0000, v98
	v_lshlrev_b32_e32 v98, 16, v99
	v_and_b32_e32 v99, 0xffff0000, v99
	v_lshlrev_b32_e32 v97, 16, v92
	v_and_b32_e32 v95, 0xffff0000, v92
	v_lshlrev_b32_e32 v90, 16, v93
	v_and_b32_e32 v91, 0xffff0000, v93
	v_lshlrev_b32_e32 v92, 16, v88
	v_and_b32_e32 v93, 0xffff0000, v88
	v_lshlrev_b32_e32 v88, 16, v89
	v_and_b32_e32 v89, 0xffff0000, v89
	v_mul_f32_e32 v96, v83, v83
	v_pk_fma_f32 v[108:109], v[82:83], v[82:83], v[96:97] op_sel_hi:[1,1,0]
	v_mul_f32_e32 v49, v95, v95
	v_mul_f32_e32 v111, v90, v90
	v_mul_f32_e32 v112, v91, v91
	v_mov_b32_e32 v109, v112
	s_nop 0
	v_mov_b32_e32 v100, v152
	v_mov_b32_e32 v101, v153
	v_mov_b32_e32 v102, v154
	v_mov_b32_e32 v103, v155
	v_pk_fma_f32 v[78:79], v[78:79], v[102:103], v[98:99]
	v_pk_fma_f32 v[34:35], v[80:81], v[100:101], v[34:35]
	v_lshlrev_b32_e32 v99, 16, v87
	v_cvt_pk_bf16_f32 v34, v34, v35
	v_cvt_pk_bf16_f32 v35, v78, v79
	global_store_dwordx2 v[24:25], v[34:35], off offset:1536 nt
	v_lshlrev_b32_e32 v98, 16, v86
	v_and_b32_e32 v87, 0xffff0000, v87
	v_and_b32_e32 v86, 0xffff0000, v86
	v_lshlrev_b32_e32 v80, 16, v84
	v_and_b32_e32 v81, 0xffff0000, v84
	v_mul_f32_e32 v24, v89, v89
	v_mul_f32_e32 v84, v93, v93
	v_mov_b32_e32 v25, v97
	v_pk_mul_f32 v[78:79], v[86:87], v[86:87]
	v_pk_fma_f32 v[104:105], v[88:89], v[88:89], v[24:25] op_sel_hi:[1,1,0]
	v_pk_fma_f32 v[84:85], v[92:93], v[92:93], v[84:85] op_sel_hi:[1,1,0]
	v_mul_f32_e32 v94, v81, v81
	v_pk_fma_f32 v[78:79], v[98:99], v[98:99], v[78:79]
	v_mov_b32_e32 v96, v84
	v_mov_b32_e32 v24, v104
	v_pk_fma_f32 v[106:107], v[80:81], v[80:81], v[94:95] op_sel_hi:[1,1,0]
	v_pk_add_f32 v[84:85], v[84:85], v[104:105]
	v_pk_add_f32 v[78:79], v[78:79], v[78:79] op_sel:[0,1] op_sel_hi:[1,0]
	v_pk_mul_f32 v[24:25], v[96:97], v[24:25]
	v_mov_b32_e32 v107, v111
	v_mov_b32_e32 v79, v49
	v_mov_b32_e32 v85, v25
	v_pk_add_f32 v[104:105], v[106:107], v[108:109]
	v_pk_add_f32 v[24:25], v[84:85], v[78:79]
	v_mov_b32_e32 v94, v97
	v_pk_add_f32 v[24:25], v[24:25], v[104:105]
	s_nop 0
	v_add_f32_e32 v24, v24, v25
	ds_bpermute_b32 v25, v206, v24
	s_waitcnt lgkmcnt(0)
	v_add_f32_e32 v24, v24, v25
	ds_bpermute_b32 v25, v207, v24
	s_waitcnt lgkmcnt(0)
	v_add_f32_e32 v24, v24, v25
	ds_bpermute_b32 v25, v208, v24
	s_waitcnt lgkmcnt(0)
	v_add_f32_e32 v24, v24, v25
	ds_bpermute_b32 v25, v209, v24
	s_waitcnt lgkmcnt(0)
	v_add_f32_e32 v24, v24, v25
	ds_bpermute_b32 v25, v210, v24
	s_waitcnt lgkmcnt(0)
	v_add_f32_e32 v25, v24, v25
	ds_bpermute_b32 v49, v211, v25
	v_lshlrev_b32_e32 v24, 16, v76
	s_waitcnt lgkmcnt(0)
; DI unsigned cvt_pk_bf16(float lo, float hi) { const f32x2 v = {lo, hi}; return __builtin_bit_cast(unsigned, __builtin_convertvector(v, bf16x2_t)); }
; DI float bflo(unsigned w) { return __uint_as_float(w << 16); }
; DI float bfhi(unsigned w) { return __uint_as_float(w & 0xffff0000u); }
; template <bool XOUT_BF, int NR>
; DI void norm_rows(const bf16_t* xin, const bf16_t* Rb, const float* gpost, void* xout, const float* gpre, bf16_t* xnb, size_t row0, size_t rstride, int lane) {
;     ...
;     for (int q = 0; q < NR; ++q) { const float rinv = __builtin_amdgcn_rsqf(ss[q] * (1.f / 1024.f) + EPS);
; #pragma unroll
;         for (int j = 0; j < 4; ++j) { const size_t off = (row0 + q * rstride) * D + 4 * lane + 256 * j;
;             const f32x4 g = *(const f32x4*)(gpost + 4 * lane + 256 * j); v[q][j] += r[q][j] * rinv * g;
;             if (XOUT_BF) { u32x2 w; w.x = cvt_pk_bf16(v[q][j][0], v[q][j][1]); w.y = cvt_pk_bf16(v[q][j][2], v[q][j][3]); __builtin_nontemporal_store(w, (u32x2*)((bf16_t*)xout + off));
;                            v[q][j] = (f32x4){bflo(w.x), bfhi(w.x), bflo(w.y), bfhi(w.y)}; }
;             else *(f32x4*)((float*)xout + off) = v[q][j];
;             s2[q] += (v[q][j][0] * v[q][j][0] + v[q][j][1] * v[q][j][1]) + (v[q][j][2] * v[q][j][2] + v[q][j][3] * v[q][j][3]); } }
;     if (xnb) {
; #pragma unroll
;         for (int o = 1; o < 64; o <<= 1)
; #pragma unroll
;             for (int q = 0; q < NR; ++q) s2[q] += __shfl_xor(s2[q], o);
	v_add_f32_e32 v25, v25, v49
	v_fmamk_f32 v25, v25, 0x3a800000, v217
	v_rsq_f32_e32 v78, v25
	v_and_b32_e32 v25, 0xffff0000, v76
	v_lshlrev_b32_e32 v76, 16, v77
	v_and_b32_e32 v77, 0xffff0000, v77
	v_pk_mul_f32 v[84:85], v[78:79], v[92:93] op_sel_hi:[0,1]
	v_pk_mul_f32 v[88:89], v[78:79], v[88:89] op_sel_hi:[0,1]
	v_pk_mul_f32 v[80:81], v[78:79], v[80:81] op_sel_hi:[0,1]
	v_pk_mul_f32 v[82:83], v[78:79], v[82:83] op_sel_hi:[0,1]
	s_nop 0
	v_mov_b32_e32 v100, v140
	v_mov_b32_e32 v101, v141
	v_mov_b32_e32 v102, v142
	v_mov_b32_e32 v103, v143
	v_pk_fma_f32 v[76:77], v[88:89], v[102:103], v[76:77]
	v_pk_fma_f32 v[24:25], v[84:85], v[100:101], v[24:25]
	v_mov_b32_e32 v84, v98
	v_cvt_pk_bf16_f32 v24, v24, v25
	v_cvt_pk_bf16_f32 v25, v76, v77
	global_store_dwordx2 v[64:65], v[24:25], off nt
	v_mov_b32_e32 v85, v86
	v_mov_b32_e32 v86, v99
	v_lshlrev_b32_e32 v76, 16, v38
	v_and_b32_e32 v77, 0xffff0000, v38
	v_lshlrev_b32_e32 v38, 16, v39
	v_and_b32_e32 v39, 0xffff0000, v39
	v_pk_mul_f32 v[84:85], v[78:79], v[84:85] op_sel_hi:[0,1]
	v_pk_mul_f32 v[86:87], v[78:79], v[86:87] op_sel_hi:[0,1]
	v_lshlrev_b32_e32 v79, 16, v74
	v_lshlrev_b32_e32 v88, 16, v54
	v_and_b32_e32 v89, 0xffff0000, v54
	v_lshlrev_b32_e32 v54, 16, v55
	v_and_b32_e32 v55, 0xffff0000, v55
	v_pk_mul_f32 v[92:93], v[78:79], v[94:95] op_sel_hi:[0,1]
	v_pk_mul_f32 v[90:91], v[78:79], v[90:91] op_sel_hi:[0,1]
	s_nop 0
	v_mov_b32_e32 v100, v144
	v_mov_b32_e32 v101, v145
	v_mov_b32_e32 v102, v146
	v_mov_b32_e32 v103, v147
	v_pk_fma_f32 v[86:87], v[86:87], v[102:103], v[38:39]
	v_pk_fma_f32 v[38:39], v[84:85], v[100:101], v[76:77]
	v_lshlrev_b32_e32 v76, 16, v44
	v_cvt_pk_bf16_f32 v38, v38, v39
	v_cvt_pk_bf16_f32 v39, v86, v87
	global_store_dwordx2 v[64:65], v[38:39], off offset:512 nt
	v_and_b32_e32 v77, 0xffff0000, v44
	v_lshlrev_b32_e32 v44, 16, v45
	v_and_b32_e32 v45, 0xffff0000, v45
	s_nop 0
	v_mov_b32_e32 v84, v148
	v_mov_b32_e32 v85, v149
	v_mov_b32_e32 v86, v150
	v_mov_b32_e32 v87, v151
	v_pk_fma_f32 v[82:83], v[82:83], v[86:87], v[44:45]
	v_pk_fma_f32 v[44:45], v[80:81], v[84:85], v[76:77]
	v_and_b32_e32 v81, 0xffff0000, v72
	v_cvt_pk_bf16_f32 v44, v44, v45
	v_cvt_pk_bf16_f32 v45, v82, v83
	global_store_dwordx2 v[64:65], v[44:45], off offset:1024 nt
	v_and_b32_e32 v83, 0xffff0000, v73
	v_and_b32_e32 v77, 0xffff0000, v74
	v_lshlrev_b32_e32 v80, 16, v72
	v_lshlrev_b32_e32 v82, 16, v73
	v_mul_f32_e32 v76, v81, v81
	v_lshlrev_b32_e32 v72, 16, v69
	v_and_b32_e32 v73, 0xffff0000, v69
	v_pk_fma_f32 v[96:97], v[80:81], v[80:81], v[76:77] op_sel_hi:[1,1,0]
	v_lshlrev_b32_e32 v74, 16, v75
	v_and_b32_e32 v75, 0xffff0000, v75
	v_mul_f32_e32 v49, v77, v77
	v_mul_f32_e32 v100, v74, v74
	v_mul_f32_e32 v101, v75, v75
	v_mov_b32_e32 v76, v79
	s_nop 0
	v_mov_b32_e32 v84, v152
	v_mov_b32_e32 v85, v153
	v_mov_b32_e32 v86, v154
	v_mov_b32_e32 v87, v155
	v_pk_fma_f32 v[86:87], v[90:91], v[86:87], v[54:55]
	v_pk_fma_f32 v[54:55], v[92:93], v[84:85], v[88:89]
	v_and_b32_e32 v85, 0xffff0000, v71
	v_cvt_pk_bf16_f32 v54, v54, v55
	v_cvt_pk_bf16_f32 v55, v86, v87
	global_store_dwordx2 v[64:65], v[54:55], off offset:1536 nt
	v_lshlrev_b32_e32 v87, 16, v71
	v_and_b32_e32 v84, 0xffff0000, v70
	v_and_b32_e32 v71, 0xffff0000, v68
	v_mul_f32_e32 v64, v83, v83
	v_mov_b32_e32 v65, v79
	v_lshlrev_b32_e32 v86, 16, v70
	v_lshlrev_b32_e32 v70, 16, v68
	v_pk_mul_f32 v[68:69], v[84:85], v[84:85]
	v_mul_f32_e32 v78, v71, v71
	v_pk_fma_f32 v[94:95], v[82:83], v[82:83], v[64:65] op_sel_hi:[1,1,0]
	v_mul_f32_e32 v92, v73, v73
	v_pk_fma_f32 v[68:69], v[86:87], v[86:87], v[68:69]
	v_pk_fma_f32 v[98:99], v[70:71], v[70:71], v[78:79] op_sel_hi:[1,1,0]
	v_mov_b32_e32 v78, v96
	v_mov_b32_e32 v64, v94
	v_pk_fma_f32 v[92:93], v[72:73], v[72:73], v[92:93] op_sel_hi:[1,1,0]
	v_pk_add_f32 v[94:95], v[96:97], v[94:95]
	v_pk_add_f32 v[68:69], v[68:69], v[68:69] op_sel:[0,1] op_sel_hi:[1,0]
	v_pk_mul_f32 v[64:65], v[78:79], v[64:65]
	v_mov_b32_e32 v99, v100
	v_mov_b32_e32 v93, v101
	v_mov_b32_e32 v69, v49
	v_mov_b32_e32 v95, v65
	v_pk_add_f32 v[92:93], v[98:99], v[92:93]
	v_pk_add_f32 v[64:65], v[94:95], v[68:69]
	s_nop 0
	v_pk_add_f32 v[64:65], v[64:65], v[92:93]
	s_nop 0
	v_add_f32_e32 v49, v64, v65
	ds_bpermute_b32 v64, v206, v49
	s_waitcnt lgkmcnt(0)
	v_add_f32_e32 v49, v49, v64
	ds_bpermute_b32 v64, v207, v49
	s_waitcnt lgkmcnt(0)
	v_add_f32_e32 v49, v49, v64
	ds_bpermute_b32 v64, v208, v49
	s_waitcnt lgkmcnt(0)
	v_add_f32_e32 v49, v49, v64
	ds_bpermute_b32 v64, v209, v49
	s_waitcnt lgkmcnt(0)
	v_add_f32_e32 v49, v49, v64
	ds_bpermute_b32 v64, v210, v49
	s_waitcnt lgkmcnt(0)
	v_add_f32_e32 v49, v49, v64
	ds_bpermute_b32 v65, v211, v49
	v_lshlrev_b32_e32 v64, 16, v66
	s_waitcnt lgkmcnt(0)
; DI unsigned cvt_pk_bf16(float lo, float hi) { const f32x2 v = {lo, hi}; return __builtin_bit_cast(unsigned, __builtin_convertvector(v, bf16x2_t)); }
; DI float bflo(unsigned w) { return __uint_as_float(w << 16); }
; DI float bfhi(unsigned w) { return __uint_as_float(w & 0xffff0000u); }
; template <bool XOUT_BF, int NR>
; DI void norm_rows(const bf16_t* xin, const bf16_t* Rb, const float* gpost, void* xout, const float* gpre, bf16_t* xnb, size_t row0, size_t rstride, int lane) {
;     ...
;     for (int q = 0; q < NR; ++q) { const float rinv = __builtin_amdgcn_rsqf(ss[q] * (1.f / 1024.f) + EPS);
; #pragma unroll
;         for (int j = 0; j < 4; ++j) { const size_t off = (row0 + q * rstride) * D + 4 * lane + 256 * j;
;             const f32x4 g = *(const f32x4*)(gpost + 4 * lane + 256 * j); v[q][j] += r[q][j] * rinv * g;
;             if (XOUT_BF) { u32x2 w; w.x = cvt_pk_bf16(v[q][j][0], v[q][j][1]); w.y = cvt_pk_bf16(v[q][j][2], v[q][j][3]); __builtin_nontemporal_store(w, (u32x2*)((bf16_t*)xout + off));
;                            v[q][j] = (f32x4){bflo(w.x), bfhi(w.x), bflo(w.y), bfhi(w.y)}; }
;             else *(f32x4*)((float*)xout + off) = v[q][j];
;             s2[q] += (v[q][j][0] * v[q][j][0] + v[q][j][1] * v[q][j][1]) + (v[q][j][2] * v[q][j][2] + v[q][j][3] * v[q][j][3]); } }
;     if (xnb) {
; #pragma unroll
;         for (int o = 1; o < 64; o <<= 1)
; #pragma unroll
;             for (int q = 0; q < NR; ++q) s2[q] += __shfl_xor(s2[q], o);
	v_add_f32_e32 v49, v49, v65
	v_fmamk_f32 v49, v49, 0x3a800000, v217
	v_rsq_f32_e32 v68, v49
	v_and_b32_e32 v65, 0xffff0000, v66
	v_lshlrev_b32_e32 v66, 16, v67
	v_and_b32_e32 v67, 0xffff0000, v67
	v_pk_mul_f32 v[80:81], v[68:69], v[80:81] op_sel_hi:[0,1]
	v_pk_mul_f32 v[82:83], v[68:69], v[82:83] op_sel_hi:[0,1]
	v_pk_mul_f32 v[70:71], v[68:69], v[70:71] op_sel_hi:[0,1]
	v_pk_mul_f32 v[72:73], v[68:69], v[72:73] op_sel_hi:[0,1]
	s_nop 0
	v_mov_b32_e32 v88, v140
	v_mov_b32_e32 v89, v141
	v_mov_b32_e32 v90, v142
	v_mov_b32_e32 v91, v143
	v_pk_fma_f32 v[66:67], v[82:83], v[90:91], v[66:67]
	v_pk_fma_f32 v[64:65], v[80:81], v[88:89], v[64:65]
	v_mov_b32_e32 v88, v86
	v_cvt_pk_bf16_f32 v64, v64, v65
	v_cvt_pk_bf16_f32 v65, v66, v67
	global_store_dwordx2 v[40:41], v[64:65], off nt
	v_mov_b32_e32 v89, v84
	v_mov_b32_e32 v84, v87
	v_lshlrev_b32_e32 v66, 16, v62
	v_and_b32_e32 v67, 0xffff0000, v62
	v_lshlrev_b32_e32 v62, 16, v63
	v_and_b32_e32 v63, 0xffff0000, v63
	v_pk_mul_f32 v[86:87], v[68:69], v[88:89] op_sel_hi:[0,1]
	v_pk_mul_f32 v[84:85], v[68:69], v[84:85] op_sel_hi:[0,1]
	v_lshlrev_b32_e32 v69, 16, v58
	v_pk_mul_f32 v[76:77], v[68:69], v[76:77] op_sel_hi:[0,1]
	v_pk_mul_f32 v[74:75], v[68:69], v[74:75] op_sel_hi:[0,1]
	s_nop 0
	v_mov_b32_e32 v80, v144
	v_mov_b32_e32 v81, v145
	v_mov_b32_e32 v82, v146
	v_mov_b32_e32 v83, v147
	v_pk_fma_f32 v[82:83], v[84:85], v[82:83], v[62:63]
	v_pk_fma_f32 v[62:63], v[86:87], v[80:81], v[66:67]
	v_lshlrev_b32_e32 v66, 16, v60
	v_cvt_pk_bf16_f32 v62, v62, v63
	v_cvt_pk_bf16_f32 v63, v82, v83
	global_store_dwordx2 v[40:41], v[62:63], off offset:512 nt
	v_and_b32_e32 v67, 0xffff0000, v60
	v_lshlrev_b32_e32 v60, 16, v61
	v_and_b32_e32 v61, 0xffff0000, v61
	v_lshlrev_b32_e32 v84, 16, v56
	v_and_b32_e32 v85, 0xffff0000, v56
	v_lshlrev_b32_e32 v56, 16, v57
	v_and_b32_e32 v57, 0xffff0000, v57
	s_nop 0
	v_mov_b32_e32 v80, v148
	v_mov_b32_e32 v81, v149
	v_mov_b32_e32 v82, v150
	v_mov_b32_e32 v83, v151
	v_pk_fma_f32 v[72:73], v[72:73], v[82:83], v[60:61]
	v_pk_fma_f32 v[60:61], v[70:71], v[80:81], v[66:67]
	v_and_b32_e32 v71, 0xffff0000, v52
	v_cvt_pk_bf16_f32 v60, v60, v61
	v_cvt_pk_bf16_f32 v61, v72, v73
	global_store_dwordx2 v[40:41], v[60:61], off offset:1024 nt
	v_and_b32_e32 v73, 0xffff0000, v53
	v_and_b32_e32 v67, 0xffff0000, v58
	v_lshlrev_b32_e32 v70, 16, v52
	v_lshlrev_b32_e32 v72, 16, v53
	v_mul_f32_e32 v66, v71, v71
	v_lshlrev_b32_e32 v52, 16, v47
	v_and_b32_e32 v53, 0xffff0000, v47
	v_pk_fma_f32 v[86:87], v[70:71], v[70:71], v[66:67] op_sel_hi:[1,1,0]
	v_lshlrev_b32_e32 v58, 16, v59
	v_and_b32_e32 v59, 0xffff0000, v59
	v_mul_f32_e32 v49, v67, v67
	v_mul_f32_e32 v90, v58, v58
	v_mul_f32_e32 v91, v59, v59
	v_mov_b32_e32 v66, v69
	s_nop 0
	v_mov_b32_e32 v80, v152
	v_mov_b32_e32 v81, v153
	v_mov_b32_e32 v82, v154
	v_mov_b32_e32 v83, v155
	v_pk_fma_f32 v[74:75], v[74:75], v[82:83], v[56:57]
	v_pk_fma_f32 v[56:57], v[76:77], v[80:81], v[84:85]
	v_lshlrev_b32_e32 v77, 16, v51
	v_cvt_pk_bf16_f32 v56, v56, v57
	v_cvt_pk_bf16_f32 v57, v74, v75
	global_store_dwordx2 v[40:41], v[56:57], off offset:1536 nt
	v_and_b32_e32 v75, 0xffff0000, v51
	v_and_b32_e32 v74, 0xffff0000, v50
	v_and_b32_e32 v51, 0xffff0000, v46
	v_mul_f32_e32 v40, v73, v73
	v_mov_b32_e32 v41, v69
	v_lshlrev_b32_e32 v76, 16, v50
	v_lshlrev_b32_e32 v50, 16, v46
	v_pk_mul_f32 v[46:47], v[74:75], v[74:75]
	v_mul_f32_e32 v68, v51, v51
	v_pk_fma_f32 v[84:85], v[72:73], v[72:73], v[40:41] op_sel_hi:[1,1,0]
	v_mul_f32_e32 v82, v53, v53
	v_pk_fma_f32 v[46:47], v[76:77], v[76:77], v[46:47]
	v_pk_fma_f32 v[88:89], v[50:51], v[50:51], v[68:69] op_sel_hi:[1,1,0]
	v_mov_b32_e32 v68, v86
	v_mov_b32_e32 v40, v84
	v_pk_fma_f32 v[82:83], v[52:53], v[52:53], v[82:83] op_sel_hi:[1,1,0]
	v_pk_add_f32 v[84:85], v[86:87], v[84:85]
	v_pk_add_f32 v[46:47], v[46:47], v[46:47] op_sel:[0,1] op_sel_hi:[1,0]
	v_pk_mul_f32 v[40:41], v[68:69], v[40:41]
	v_mov_b32_e32 v89, v90
	v_mov_b32_e32 v83, v91
	v_mov_b32_e32 v47, v49
	v_mov_b32_e32 v85, v41
	v_pk_add_f32 v[82:83], v[88:89], v[82:83]
	v_pk_add_f32 v[40:41], v[84:85], v[46:47]
	s_nop 0
	v_pk_add_f32 v[40:41], v[40:41], v[82:83]
	s_nop 0
	v_add_f32_e32 v40, v40, v41
	ds_bpermute_b32 v41, v206, v40
	s_waitcnt lgkmcnt(0)
	v_add_f32_e32 v40, v40, v41
	ds_bpermute_b32 v41, v207, v40
	s_waitcnt lgkmcnt(0)
	v_add_f32_e32 v40, v40, v41
	ds_bpermute_b32 v41, v208, v40
	s_waitcnt lgkmcnt(0)
	v_add_f32_e32 v40, v40, v41
	ds_bpermute_b32 v41, v209, v40
	s_waitcnt lgkmcnt(0)
	v_add_f32_e32 v40, v40, v41
	ds_bpermute_b32 v41, v210, v40
	s_waitcnt lgkmcnt(0)
	v_add_f32_e32 v41, v40, v41
	ds_bpermute_b32 v46, v211, v41
	v_lshlrev_b32_e32 v40, 16, v42
	s_waitcnt lgkmcnt(0)
; DI unsigned cvt_pk_bf16(float lo, float hi) { const f32x2 v = {lo, hi}; return __builtin_bit_cast(unsigned, __builtin_convertvector(v, bf16x2_t)); }
; DI float bflo(unsigned w) { return __uint_as_float(w << 16); }
; DI float bfhi(unsigned w) { return __uint_as_float(w & 0xffff0000u); }
; template <bool XOUT_BF, int NR>
; DI void norm_rows(const bf16_t* xin, const bf16_t* Rb, const float* gpost, void* xout, const float* gpre, bf16_t* xnb, size_t row0, size_t rstride, int lane) {
;     ...
;     for (int q = 0; q < NR; ++q) { const float rinv = __builtin_amdgcn_rsqf(ss[q] * (1.f / 1024.f) + EPS);
; #pragma unroll
;         for (int j = 0; j < 4; ++j) { const size_t off = (row0 + q * rstride) * D + 4 * lane + 256 * j;
;             const f32x4 g = *(const f32x4*)(gpost + 4 * lane + 256 * j); v[q][j] += r[q][j] * rinv * g;
;             if (XOUT_BF) { u32x2 w; w.x = cvt_pk_bf16(v[q][j][0], v[q][j][1]); w.y = cvt_pk_bf16(v[q][j][2], v[q][j][3]); __builtin_nontemporal_store(w, (u32x2*)((bf16_t*)xout + off));
;                            v[q][j] = (f32x4){bflo(w.x), bfhi(w.x), bflo(w.y), bfhi(w.y)}; }
;             else *(f32x4*)((float*)xout + off) = v[q][j];
;             s2[q] += (v[q][j][0] * v[q][j][0] + v[q][j][1] * v[q][j][1]) + (v[q][j][2] * v[q][j][2] + v[q][j][3] * v[q][j][3]); } }
;     if (xnb) {
; #pragma unroll
;         for (int o = 1; o < 64; o <<= 1)
; #pragma unroll
;             for (int q = 0; q < NR; ++q) s2[q] += __shfl_xor(s2[q], o);
; #pragma unroll
;         for (int q = 0; q < NR; ++q) { const float rinv = __builtin_amdgcn_rsqf(s2[q] * (1.f / 1024.f) + EPS);
; #pragma unroll
;             for (int j = 0; j < 4; ++j) { const size_t off = (row0 + q * rstride) * D + 4 * lane + 256 * j;
;                 const f32x4 g = *(const f32x4*)(gpre + 4 * lane + 256 * j); const f32x4 o = v[q][j] * rinv * g;
;                 u32x2 w; w.x = cvt_pk_bf16(o[0], o[1]); w.y = cvt_pk_bf16(o[2], o[3]); *(u32x2*)(xnb + off) = w; } }
	v_add_f32_e32 v41, v41, v46
	v_fmamk_f32 v41, v41, 0x3a800000, v217
	v_rsq_f32_e32 v46, v41
	v_and_b32_e32 v41, 0xffff0000, v42
	v_lshlrev_b32_e32 v42, 16, v43
	v_and_b32_e32 v43, 0xffff0000, v43
	v_pk_mul_f32 v[70:71], v[46:47], v[70:71] op_sel_hi:[0,1]
	v_pk_mul_f32 v[72:73], v[46:47], v[72:73] op_sel_hi:[0,1]
	v_pk_mul_f32 v[50:51], v[46:47], v[50:51] op_sel_hi:[0,1]
	v_pk_mul_f32 v[52:53], v[46:47], v[52:53] op_sel_hi:[0,1]
	v_pk_mul_f32 v[66:67], v[46:47], v[66:67] op_sel_hi:[0,1]
	s_nop 0
	v_mov_b32_e32 v78, v140
	v_mov_b32_e32 v79, v141
	v_mov_b32_e32 v80, v142
	v_mov_b32_e32 v81, v143
	v_pk_fma_f32 v[42:43], v[72:73], v[80:81], v[42:43]
	v_pk_fma_f32 v[40:41], v[70:71], v[78:79], v[40:41]
	v_mov_b32_e32 v78, v76
	v_cvt_pk_bf16_f32 v40, v40, v41
	v_cvt_pk_bf16_f32 v41, v42, v43
	global_store_dwordx2 v[26:27], v[40:41], off nt
	v_mov_b32_e32 v79, v74
	v_mov_b32_e32 v74, v77
	v_lshlrev_b32_e32 v42, 16, v36
	v_and_b32_e32 v43, 0xffff0000, v36
	v_lshlrev_b32_e32 v36, 16, v37
	v_and_b32_e32 v37, 0xffff0000, v37
	v_pk_mul_f32 v[76:77], v[46:47], v[78:79] op_sel_hi:[0,1]
	v_pk_mul_f32 v[74:75], v[46:47], v[74:75] op_sel_hi:[0,1]
	v_pk_mul_f32 v[46:47], v[46:47], v[58:59] op_sel_hi:[0,1]
	s_nop 0
	v_mov_b32_e32 v70, v144
	v_mov_b32_e32 v71, v145
	v_mov_b32_e32 v72, v146
	v_mov_b32_e32 v73, v147
	v_pk_fma_f32 v[72:73], v[74:75], v[72:73], v[36:37]
	v_pk_fma_f32 v[36:37], v[76:77], v[70:71], v[42:43]
	v_lshlrev_b32_e32 v42, 16, v30
	v_cvt_pk_bf16_f32 v36, v36, v37
	v_cvt_pk_bf16_f32 v37, v72, v73
	global_store_dwordx2 v[26:27], v[36:37], off offset:512 nt
	v_and_b32_e32 v43, 0xffff0000, v30
	v_lshlrev_b32_e32 v30, 16, v31
	v_and_b32_e32 v31, 0xffff0000, v31
	s_nop 0
	v_mov_b32_e32 v70, v148
	v_mov_b32_e32 v71, v149
	v_mov_b32_e32 v72, v150
	v_mov_b32_e32 v73, v151
	v_pk_fma_f32 v[52:53], v[52:53], v[72:73], v[30:31]
	v_pk_fma_f32 v[30:31], v[50:51], v[70:71], v[42:43]
	v_lshlrev_b32_e32 v42, 16, v28
	v_cvt_pk_bf16_f32 v30, v30, v31
	v_cvt_pk_bf16_f32 v31, v52, v53
	global_store_dwordx2 v[26:27], v[30:31], off offset:1024 nt
	v_and_b32_e32 v43, 0xffff0000, v28
	v_lshlrev_b32_e32 v28, 16, v29
	v_and_b32_e32 v29, 0xffff0000, v29
	s_nop 0
	v_mov_b32_e32 v50, v152
	v_mov_b32_e32 v51, v153
	v_mov_b32_e32 v52, v154
	v_mov_b32_e32 v53, v155
	v_pk_fma_f32 v[46:47], v[46:47], v[52:53], v[28:29]
	v_pk_fma_f32 v[28:29], v[66:67], v[50:51], v[42:43]
	s_nop 0
	v_cvt_pk_bf16_f32 v28, v28, v29
	v_cvt_pk_bf16_f32 v29, v46, v47
	global_store_dwordx2 v[26:27], v[28:29], off offset:1536 nt
	s_cbranch_vccnz .LBB0_1586
	v_lshlrev_b32_e32 v27, 16, v33
	v_lshlrev_b32_e32 v26, 16, v32
	v_and_b32_e32 v33, 0xffff0000, v33
	v_and_b32_e32 v32, 0xffff0000, v32
	v_and_b32_e32 v59, 0xffff0000, v1
	v_and_b32_e32 v58, 0xffff0000, v0
	v_lshlrev_b32_e32 v66, 16, v2
	v_and_b32_e32 v67, 0xffff0000, v2
	v_lshlrev_b32_e32 v69, 16, v34
	v_pk_mul_f32 v[42:43], v[32:33], v[32:33]
	v_lshlrev_b32_e32 v47, 16, v1
	v_lshlrev_b32_e32 v46, 16, v0
	v_pk_mul_f32 v[0:1], v[58:59], v[58:59]
	v_mul_f32_e32 v68, v66, v66
	v_mul_f32_e32 v2, v67, v67
	v_lshlrev_b32_e32 v70, 16, v3
	v_and_b32_e32 v71, 0xffff0000, v3
	v_mov_b32_e32 v3, v69
	v_pk_fma_f32 v[42:43], v[26:27], v[26:27], v[42:43]
	v_pk_fma_f32 v[0:1], v[46:47], v[46:47], v[0:1]
	v_and_b32_e32 v73, 0xffff0000, v34
	v_lshlrev_b32_e32 v34, 16, v35
	v_and_b32_e32 v35, 0xffff0000, v35
	v_pk_add_f32 v[2:3], v[68:69], v[2:3]
	v_pk_mul_f32 v[74:75], v[68:69], v[68:69]
	v_mul_f32_e32 v68, v71, v71
	v_mul_f32_e32 v49, v73, v73
	v_mul_f32_e32 v72, v34, v34
	v_mul_f32_e32 v76, v35, v35
	v_mov_b32_e32 v3, v75
	v_pk_fma_f32 v[74:75], v[70:71], v[70:71], v[68:69] op_sel_hi:[1,1,0]
	v_pk_add_f32 v[42:43], v[42:43], v[42:43] op_sel:[0,1] op_sel_hi:[1,0]
	v_pk_add_f32 v[0:1], v[0:1], v[0:1] op_sel:[0,1] op_sel_hi:[1,0]
	v_mov_b32_e32 v75, v49
	v_mov_b32_e32 v43, v72
	v_mov_b32_e32 v1, v76
	v_pk_add_f32 v[2:3], v[2:3], v[74:75]
	v_pk_add_f32 v[0:1], v[42:43], v[0:1]
	v_lshl_add_u64 v[42:43], v[10:11], 0, s[50:51]
	v_pk_add_f32 v[0:1], v[2:3], v[0:1]
	v_mov_b32_e32 v72, v69
	v_add_f32_e32 v0, v0, v1
	ds_bpermute_b32 v1, v206, v0
	s_waitcnt lgkmcnt(0)
	v_add_f32_e32 v0, v0, v1
	ds_bpermute_b32 v1, v207, v0
	s_waitcnt lgkmcnt(0)
	v_add_f32_e32 v0, v0, v1
	ds_bpermute_b32 v1, v208, v0
	s_waitcnt lgkmcnt(0)
	v_add_f32_e32 v0, v0, v1
	ds_bpermute_b32 v1, v209, v0
	s_waitcnt lgkmcnt(0)
	v_add_f32_e32 v0, v0, v1
	ds_bpermute_b32 v1, v210, v0
	s_waitcnt lgkmcnt(0)
	v_add_f32_e32 v0, v0, v1
	ds_bpermute_b32 v1, v211, v0
	s_waitcnt lgkmcnt(0)
; DI unsigned cvt_pk_bf16(float lo, float hi) { const f32x2 v = {lo, hi}; return __builtin_bit_cast(unsigned, __builtin_convertvector(v, bf16x2_t)); }
; template <bool XOUT_BF, int NR>
; DI void norm_rows(const bf16_t* xin, const bf16_t* Rb, const float* gpost, void* xout, const float* gpre, bf16_t* xnb, size_t row0, size_t rstride, int lane) {
;     ...
;     if (xnb) {
; #pragma unroll
;         for (int o = 1; o < 64; o <<= 1)
; #pragma unroll
;             for (int q = 0; q < NR; ++q) s2[q] += __shfl_xor(s2[q], o);
; #pragma unroll
;         for (int q = 0; q < NR; ++q) { const float rinv = __builtin_amdgcn_rsqf(s2[q] * (1.f / 1024.f) + EPS);
; #pragma unroll
;             for (int j = 0; j < 4; ++j) { const size_t off = (row0 + q * rstride) * D + 4 * lane + 256 * j;
;                 const f32x4 g = *(const f32x4*)(gpre + 4 * lane + 256 * j); const f32x4 o = v[q][j] * rinv * g;
;                 u32x2 w; w.x = cvt_pk_bf16(o[0], o[1]); w.y = cvt_pk_bf16(o[2], o[3]); *(u32x2*)(xnb + off) = w; } }
	v_add_f32_e32 v0, v0, v1
	v_fmamk_f32 v0, v0, 0x3a800000, v217
	v_rsq_f32_e32 v68, v0
	v_mov_b32_e32 v0, v26
	v_mov_b32_e32 v1, v32
	v_mov_b32_e32 v32, v27
	v_pk_mul_f32 v[0:1], v[68:69], v[0:1] op_sel_hi:[0,1]
	v_pk_mul_f32 v[2:3], v[68:69], v[32:33] op_sel_hi:[0,1]
	s_nop 0
	v_mov_b32_e32 v50, v156
	v_mov_b32_e32 v51, v157
	v_mov_b32_e32 v52, v158
	v_mov_b32_e32 v53, v159
	v_pk_mul_f32 v[2:3], v[52:53], v[2:3]
	v_pk_mul_f32 v[0:1], v[50:51], v[0:1]
	v_mov_b32_e32 v26, v46
	v_cvt_pk_bf16_f32 v0, v0, v1
	v_cvt_pk_bf16_f32 v1, v2, v3
	global_store_dwordx2 v[42:43], v[0:1], off
	v_mov_b32_e32 v27, v58
	v_mov_b32_e32 v58, v47
	v_pk_mul_f32 v[26:27], v[68:69], v[26:27] op_sel_hi:[0,1]
	v_pk_mul_f32 v[32:33], v[68:69], v[58:59] op_sel_hi:[0,1]
	v_pk_mul_f32 v[46:47], v[72:73], v[68:69] op_sel_hi:[1,0]
	v_pk_mul_f32 v[34:35], v[34:35], v[68:69] op_sel_hi:[1,0]
	v_lshlrev_b32_e32 v50, 16, v55
	v_and_b32_e32 v51, 0xffff0000, v55
	v_mul_f32_e32 v72, v50, v50
	v_mul_f32_e32 v73, v51, v51
	s_nop 0
	v_mov_b32_e32 v0, v160
	v_mov_b32_e32 v1, v161
	v_mov_b32_e32 v2, v162
	v_mov_b32_e32 v3, v163
	v_pk_mul_f32 v[2:3], v[2:3], v[32:33]
	v_pk_mul_f32 v[0:1], v[0:1], v[26:27]
	v_pk_mul_f32 v[26:27], v[66:67], v[68:69] op_sel_hi:[1,0]
	v_cvt_pk_bf16_f32 v0, v0, v1
	v_cvt_pk_bf16_f32 v1, v2, v3
	global_store_dwordx2 v[42:43], v[0:1], off offset:512
	v_pk_mul_f32 v[32:33], v[70:71], v[68:69] op_sel_hi:[1,0]
	s_nop 0
	v_mov_b32_e32 v0, v164
	v_mov_b32_e32 v1, v165
	v_mov_b32_e32 v2, v166
	v_mov_b32_e32 v3, v167
	v_pk_mul_f32 v[0:1], v[0:1], v[26:27]
	v_pk_mul_f32 v[2:3], v[2:3], v[32:33]
	v_cvt_pk_bf16_f32 v0, v0, v1
	v_cvt_pk_bf16_f32 v1, v2, v3
	global_store_dwordx2 v[42:43], v[0:1], off offset:1024
	v_lshlrev_b32_e32 v26, 16, v24
	v_and_b32_e32 v27, 0xffff0000, v24
	v_lshlrev_b32_e32 v24, 16, v25
	v_and_b32_e32 v25, 0xffff0000, v25
	v_lshlrev_b32_e32 v33, 16, v39
	v_lshlrev_b32_e32 v32, 16, v38
	v_and_b32_e32 v39, 0xffff0000, v39
	v_and_b32_e32 v38, 0xffff0000, v38
	v_pk_mul_f32 v[52:53], v[38:39], v[38:39]
	s_nop 0
	v_mov_b32_e32 v0, v168
	v_mov_b32_e32 v1, v169
	v_mov_b32_e32 v2, v170
	v_mov_b32_e32 v3, v171
	v_pk_mul_f32 v[2:3], v[34:35], v[2:3]
	v_pk_mul_f32 v[0:1], v[46:47], v[0:1]
	v_lshlrev_b32_e32 v34, 16, v44
	v_cvt_pk_bf16_f32 v0, v0, v1
	v_cvt_pk_bf16_f32 v1, v2, v3
	global_store_dwordx2 v[42:43], v[0:1], off offset:1536
	v_and_b32_e32 v35, 0xffff0000, v44
	v_lshlrev_b32_e32 v42, 16, v45
	v_and_b32_e32 v43, 0xffff0000, v45
	v_lshlrev_b32_e32 v45, 16, v54
	v_and_b32_e32 v47, 0xffff0000, v54
	v_mul_f32_e32 v44, v25, v25
	v_mul_f32_e32 v46, v27, v27
	v_mov_b32_e32 v55, v45
	v_mul_f32_e32 v54, v35, v35
	v_pk_fma_f32 v[66:67], v[24:25], v[24:25], v[44:45] op_sel_hi:[1,1,0]
	v_pk_fma_f32 v[68:69], v[26:27], v[26:27], v[46:47] op_sel_hi:[1,1,0]
	v_mul_f32_e32 v58, v43, v43
	v_pk_fma_f32 v[52:53], v[32:33], v[32:33], v[52:53]
	v_pk_fma_f32 v[70:71], v[34:35], v[34:35], v[54:55] op_sel_hi:[1,1,0]
	v_mov_b32_e32 v44, v68
	v_mov_b32_e32 v54, v66
	v_mul_f32_e32 v49, v47, v47
	v_pk_fma_f32 v[58:59], v[42:43], v[42:43], v[58:59] op_sel_hi:[1,1,0]
	v_pk_add_f32 v[66:67], v[68:69], v[66:67]
	v_pk_add_f32 v[52:53], v[52:53], v[52:53] op_sel:[0,1] op_sel_hi:[1,0]
	v_pk_mul_f32 v[54:55], v[44:45], v[54:55]
	v_mov_b32_e32 v71, v72
	v_mov_b32_e32 v59, v73
	v_mov_b32_e32 v53, v49
	v_mov_b32_e32 v67, v55
	v_pk_add_f32 v[58:59], v[70:71], v[58:59]
	v_pk_add_f32 v[52:53], v[66:67], v[52:53]
	s_nop 0
	v_pk_add_f32 v[52:53], v[52:53], v[58:59]
	s_nop 0
	v_add_f32_e32 v44, v52, v53
	ds_bpermute_b32 v46, v206, v44
	v_lshl_add_u64 v[52:53], v[22:23], 0, s[50:51]
	s_waitcnt lgkmcnt(0)
	v_add_f32_e32 v44, v44, v46
	ds_bpermute_b32 v46, v207, v44
	s_waitcnt lgkmcnt(0)
	v_add_f32_e32 v44, v44, v46
	ds_bpermute_b32 v46, v208, v44
	s_waitcnt lgkmcnt(0)
	v_add_f32_e32 v44, v44, v46
	ds_bpermute_b32 v46, v209, v44
	s_waitcnt lgkmcnt(0)
	v_add_f32_e32 v44, v44, v46
	ds_bpermute_b32 v46, v210, v44
	s_waitcnt lgkmcnt(0)
	v_add_f32_e32 v44, v44, v46
	ds_bpermute_b32 v46, v211, v44
	s_waitcnt lgkmcnt(0)
	v_add_f32_e32 v44, v44, v46
	v_fmamk_f32 v44, v44, 0x3a800000, v217
	v_rsq_f32_e32 v44, v44
	v_mov_b32_e32 v46, v45
	v_pk_mul_f32 v[26:27], v[44:45], v[26:27] op_sel_hi:[0,1]
	v_pk_mul_f32 v[24:25], v[44:45], v[24:25] op_sel_hi:[0,1]
	s_nop 0
	v_mov_b32_e32 v0, v156
	v_mov_b32_e32 v1, v157
	v_mov_b32_e32 v2, v158
	v_mov_b32_e32 v3, v159
	v_pk_mul_f32 v[2:3], v[24:25], v[2:3]
	v_pk_mul_f32 v[0:1], v[26:27], v[0:1]
	v_mov_b32_e32 v24, v32
	v_cvt_pk_bf16_f32 v0, v0, v1
	v_cvt_pk_bf16_f32 v1, v2, v3
	global_store_dwordx2 v[52:53], v[0:1], off
	v_mov_b32_e32 v25, v38
	v_mov_b32_e32 v38, v33
	v_pk_mul_f32 v[24:25], v[44:45], v[24:25] op_sel_hi:[0,1]
	v_pk_mul_f32 v[26:27], v[44:45], v[38:39] op_sel_hi:[0,1]
	v_pk_mul_f32 v[38:39], v[46:47], v[44:45] op_sel_hi:[1,0]
	v_and_b32_e32 v47, 0xffff0000, v56
	v_lshlrev_b32_e32 v33, 16, v63
	v_lshlrev_b32_e32 v32, 16, v62
	v_mul_f32_e32 v49, v47, v47
	s_nop 0
	v_mov_b32_e32 v0, v160
	v_mov_b32_e32 v1, v161
	v_mov_b32_e32 v2, v162
	v_mov_b32_e32 v3, v163
	v_pk_mul_f32 v[2:3], v[26:27], v[2:3]
	v_pk_mul_f32 v[0:1], v[24:25], v[0:1]
	v_pk_mul_f32 v[24:25], v[44:45], v[34:35] op_sel_hi:[0,1]
	v_cvt_pk_bf16_f32 v0, v0, v1
	v_cvt_pk_bf16_f32 v1, v2, v3
	global_store_dwordx2 v[52:53], v[0:1], off offset:512
	v_pk_mul_f32 v[26:27], v[44:45], v[42:43] op_sel_hi:[0,1]
	v_pk_mul_f32 v[42:43], v[50:51], v[44:45] op_sel_hi:[1,0]
	v_and_b32_e32 v35, 0xffff0000, v63
	v_and_b32_e32 v34, 0xffff0000, v62
	v_lshlrev_b32_e32 v45, 16, v56
	v_mov_b32_e32 v55, v45
	v_lshlrev_b32_e32 v50, 16, v57
	v_and_b32_e32 v51, 0xffff0000, v57
	s_nop 0
	v_mov_b32_e32 v0, v164
; DI unsigned cvt_pk_bf16(float lo, float hi) { const f32x2 v = {lo, hi}; return __builtin_bit_cast(unsigned, __builtin_convertvector(v, bf16x2_t)); }
; template <bool XOUT_BF, int NR>
; DI void norm_rows(const bf16_t* xin, const bf16_t* Rb, const float* gpost, void* xout, const float* gpre, bf16_t* xnb, size_t row0, size_t rstride, int lane) {
;     ...
;     if (xnb) {
; #pragma unroll
;         for (int o = 1; o < 64; o <<= 1)
; #pragma unroll
;             for (int q = 0; q < NR; ++q) s2[q] += __shfl_xor(s2[q], o);
; #pragma unroll
;         for (int q = 0; q < NR; ++q) { const float rinv = __builtin_amdgcn_rsqf(s2[q] * (1.f / 1024.f) + EPS);
; #pragma unroll
;             for (int j = 0; j < 4; ++j) { const size_t off = (row0 + q * rstride) * D + 4 * lane + 256 * j;
;                 const f32x4 g = *(const f32x4*)(gpre + 4 * lane + 256 * j); const f32x4 o = v[q][j] * rinv * g;
;                 u32x2 w; w.x = cvt_pk_bf16(o[0], o[1]); w.y = cvt_pk_bf16(o[2], o[3]); *(u32x2*)(xnb + off) = w; } }
	v_mov_b32_e32 v1, v165
	v_mov_b32_e32 v2, v166
	v_mov_b32_e32 v3, v167
	v_pk_mul_f32 v[2:3], v[26:27], v[2:3]
	v_pk_mul_f32 v[0:1], v[24:25], v[0:1]
	v_and_b32_e32 v25, 0xffff0000, v64
	v_cvt_pk_bf16_f32 v0, v0, v1
	v_cvt_pk_bf16_f32 v1, v2, v3
	global_store_dwordx2 v[52:53], v[0:1], off offset:1024
	v_and_b32_e32 v27, 0xffff0000, v65
	v_lshlrev_b32_e32 v24, 16, v64
	v_lshlrev_b32_e32 v26, 16, v65
	v_mul_f32_e32 v44, v27, v27
	v_mul_f32_e32 v46, v25, v25
	v_pk_fma_f32 v[58:59], v[26:27], v[26:27], v[44:45] op_sel_hi:[1,1,0]
	v_mul_f32_e32 v64, v50, v50
	v_mul_f32_e32 v65, v51, v51
	s_nop 0
	v_mov_b32_e32 v0, v168
	v_mov_b32_e32 v1, v169
	v_mov_b32_e32 v2, v170
	v_mov_b32_e32 v3, v171
	v_pk_mul_f32 v[2:3], v[42:43], v[2:3]
	v_pk_mul_f32 v[0:1], v[38:39], v[0:1]
	v_and_b32_e32 v39, 0xffff0000, v60
	v_cvt_pk_bf16_f32 v0, v0, v1
	v_cvt_pk_bf16_f32 v1, v2, v3
	global_store_dwordx2 v[52:53], v[0:1], off offset:1536
	v_lshlrev_b32_e32 v38, 16, v60
	v_lshlrev_b32_e32 v42, 16, v61
	v_and_b32_e32 v43, 0xffff0000, v61
	v_pk_mul_f32 v[52:53], v[34:35], v[34:35]
	v_mul_f32_e32 v54, v39, v39
	v_pk_fma_f32 v[60:61], v[24:25], v[24:25], v[46:47] op_sel_hi:[1,1,0]
	v_mul_f32_e32 v56, v43, v43
	v_pk_fma_f32 v[52:53], v[32:33], v[32:33], v[52:53]
	v_pk_fma_f32 v[62:63], v[38:39], v[38:39], v[54:55] op_sel_hi:[1,1,0]
	v_mov_b32_e32 v44, v60
	v_mov_b32_e32 v54, v58
	v_pk_fma_f32 v[56:57], v[42:43], v[42:43], v[56:57] op_sel_hi:[1,1,0]
	v_pk_add_f32 v[58:59], v[60:61], v[58:59]
	v_pk_add_f32 v[52:53], v[52:53], v[52:53] op_sel:[0,1] op_sel_hi:[1,0]
	v_pk_mul_f32 v[54:55], v[44:45], v[54:55]
	v_mov_b32_e32 v63, v64
	v_mov_b32_e32 v57, v65
	v_mov_b32_e32 v53, v49
	v_mov_b32_e32 v59, v55
	v_pk_add_f32 v[56:57], v[62:63], v[56:57]
	v_pk_add_f32 v[52:53], v[58:59], v[52:53]
	s_nop 0
	v_pk_add_f32 v[52:53], v[52:53], v[56:57]
	s_nop 0
	v_add_f32_e32 v44, v52, v53
	ds_bpermute_b32 v46, v206, v44
	v_lshl_add_u64 v[52:53], v[14:15], 0, s[50:51]
	s_waitcnt lgkmcnt(0)
	v_add_f32_e32 v44, v44, v46
	ds_bpermute_b32 v46, v207, v44
	s_waitcnt lgkmcnt(0)
	v_add_f32_e32 v44, v44, v46
	ds_bpermute_b32 v46, v208, v44
	s_waitcnt lgkmcnt(0)
	v_add_f32_e32 v44, v44, v46
	ds_bpermute_b32 v46, v209, v44
	s_waitcnt lgkmcnt(0)
	v_add_f32_e32 v44, v44, v46
	ds_bpermute_b32 v46, v210, v44
	s_waitcnt lgkmcnt(0)
	v_add_f32_e32 v44, v44, v46
	ds_bpermute_b32 v46, v211, v44
	s_waitcnt lgkmcnt(0)
; DI unsigned cvt_pk_bf16(float lo, float hi) { const f32x2 v = {lo, hi}; return __builtin_bit_cast(unsigned, __builtin_convertvector(v, bf16x2_t)); }
; template <bool XOUT_BF, int NR>
; DI void norm_rows(const bf16_t* xin, const bf16_t* Rb, const float* gpost, void* xout, const float* gpre, bf16_t* xnb, size_t row0, size_t rstride, int lane) {
;     ...
;     if (xnb) {
; #pragma unroll
;         for (int o = 1; o < 64; o <<= 1)
; #pragma unroll
;             for (int q = 0; q < NR; ++q) s2[q] += __shfl_xor(s2[q], o);
; #pragma unroll
;         for (int q = 0; q < NR; ++q) { const float rinv = __builtin_amdgcn_rsqf(s2[q] * (1.f / 1024.f) + EPS);
; #pragma unroll
;             for (int j = 0; j < 4; ++j) { const size_t off = (row0 + q * rstride) * D + 4 * lane + 256 * j;
;                 const f32x4 g = *(const f32x4*)(gpre + 4 * lane + 256 * j); const f32x4 o = v[q][j] * rinv * g;
;                 u32x2 w; w.x = cvt_pk_bf16(o[0], o[1]); w.y = cvt_pk_bf16(o[2], o[3]); *(u32x2*)(xnb + off) = w; } }
	v_add_f32_e32 v44, v44, v46
	v_fmamk_f32 v44, v44, 0x3a800000, v217
	v_rsq_f32_e32 v44, v44
	v_mov_b32_e32 v46, v45
	v_pk_mul_f32 v[24:25], v[44:45], v[24:25] op_sel_hi:[0,1]
	v_pk_mul_f32 v[26:27], v[44:45], v[26:27] op_sel_hi:[0,1]
	s_nop 0
	v_mov_b32_e32 v0, v156
	v_mov_b32_e32 v1, v157
	v_mov_b32_e32 v2, v158
	v_mov_b32_e32 v3, v159
	v_pk_mul_f32 v[2:3], v[26:27], v[2:3]
	v_pk_mul_f32 v[0:1], v[24:25], v[0:1]
	v_mov_b32_e32 v24, v32
	v_cvt_pk_bf16_f32 v0, v0, v1
	v_cvt_pk_bf16_f32 v1, v2, v3
	global_store_dwordx2 v[52:53], v[0:1], off
	v_mov_b32_e32 v25, v34
	v_mov_b32_e32 v34, v33
	v_pk_mul_f32 v[24:25], v[44:45], v[24:25] op_sel_hi:[0,1]
	v_pk_mul_f32 v[26:27], v[44:45], v[34:35] op_sel_hi:[0,1]
	v_lshlrev_b32_e32 v33, 16, v37
	v_and_b32_e32 v35, 0xffff0000, v37
	v_and_b32_e32 v34, 0xffff0000, v36
	v_and_b32_e32 v37, 0xffff0000, v30
	v_lshlrev_b32_e32 v32, 16, v36
	v_lshlrev_b32_e32 v36, 16, v30
	v_lshlrev_b32_e32 v30, 16, v31
	v_and_b32_e32 v31, 0xffff0000, v31
	s_nop 0
	v_mov_b32_e32 v0, v160
	v_mov_b32_e32 v1, v161
	v_mov_b32_e32 v2, v162
	v_mov_b32_e32 v3, v163
	v_pk_mul_f32 v[2:3], v[26:27], v[2:3]
	v_pk_mul_f32 v[0:1], v[24:25], v[0:1]
	v_pk_mul_f32 v[24:25], v[44:45], v[38:39] op_sel_hi:[0,1]
	v_cvt_pk_bf16_f32 v0, v0, v1
	v_cvt_pk_bf16_f32 v1, v2, v3
	global_store_dwordx2 v[52:53], v[0:1], off offset:512
	v_pk_mul_f32 v[26:27], v[44:45], v[42:43] op_sel_hi:[0,1]
	v_pk_mul_f32 v[38:39], v[46:47], v[44:45] op_sel_hi:[1,0]
	v_pk_mul_f32 v[42:43], v[34:35], v[34:35]
	v_mul_f32_e32 v46, v31, v31
	v_pk_fma_f32 v[42:43], v[32:33], v[32:33], v[42:43]
	v_pk_fma_f32 v[46:47], v[30:31], v[30:31], v[46:47] op_sel_hi:[1,1,0]
	v_pk_add_f32 v[42:43], v[42:43], v[42:43] op_sel:[0,1] op_sel_hi:[1,0]
	s_nop 0
	v_mov_b32_e32 v0, v164
	v_mov_b32_e32 v1, v165
	v_mov_b32_e32 v2, v166
	v_mov_b32_e32 v3, v167
	v_pk_mul_f32 v[2:3], v[26:27], v[2:3]
	v_pk_mul_f32 v[0:1], v[24:25], v[0:1]
	v_lshlrev_b32_e32 v24, 16, v40
	v_cvt_pk_bf16_f32 v0, v0, v1
	v_cvt_pk_bf16_f32 v1, v2, v3
	global_store_dwordx2 v[52:53], v[0:1], off offset:1024
	v_and_b32_e32 v25, 0xffff0000, v40
	v_lshlrev_b32_e32 v26, 16, v41
	v_and_b32_e32 v27, 0xffff0000, v41
	v_pk_mul_f32 v[40:41], v[50:51], v[44:45] op_sel_hi:[1,0]
	v_mul_f32_e32 v44, v37, v37
	s_nop 0
	v_mov_b32_e32 v0, v168
	v_mov_b32_e32 v1, v169
	v_mov_b32_e32 v2, v170
	v_mov_b32_e32 v3, v171
	v_pk_mul_f32 v[2:3], v[40:41], v[2:3]
	v_pk_mul_f32 v[0:1], v[38:39], v[0:1]
	v_lshlrev_b32_e32 v39, 16, v28
	v_cvt_pk_bf16_f32 v0, v0, v1
	v_cvt_pk_bf16_f32 v1, v2, v3
	global_store_dwordx2 v[52:53], v[0:1], off offset:1536
	v_and_b32_e32 v41, 0xffff0000, v28
	v_mul_f32_e32 v38, v27, v27
	v_mul_f32_e32 v40, v25, v25
	v_mov_b32_e32 v45, v39
	v_pk_fma_f32 v[50:51], v[26:27], v[26:27], v[38:39] op_sel_hi:[1,1,0]
	v_pk_fma_f32 v[52:53], v[24:25], v[24:25], v[40:41] op_sel_hi:[1,1,0]
	v_lshlrev_b32_e32 v28, 16, v29
	v_and_b32_e32 v29, 0xffff0000, v29
	v_pk_fma_f32 v[54:55], v[36:37], v[36:37], v[44:45] op_sel_hi:[1,1,0]
	v_mov_b32_e32 v38, v52
	v_mov_b32_e32 v44, v50
	v_mul_f32_e32 v49, v41, v41
	v_mul_f32_e32 v56, v28, v28
	v_mul_f32_e32 v57, v29, v29
	v_pk_add_f32 v[50:51], v[52:53], v[50:51]
	v_pk_mul_f32 v[44:45], v[38:39], v[44:45]
	v_mov_b32_e32 v55, v56
	v_mov_b32_e32 v47, v57
	v_mov_b32_e32 v43, v49
	v_mov_b32_e32 v51, v45
	v_pk_add_f32 v[46:47], v[54:55], v[46:47]
	v_pk_add_f32 v[42:43], v[50:51], v[42:43]
	s_nop 0
	v_pk_add_f32 v[42:43], v[42:43], v[46:47]
	s_nop 0
	v_add_f32_e32 v38, v42, v43
	ds_bpermute_b32 v40, v206, v38
	v_lshl_add_u64 v[42:43], v[20:21], 0, s[50:51]
	s_waitcnt lgkmcnt(0)
	v_add_f32_e32 v38, v38, v40
	ds_bpermute_b32 v40, v207, v38
	s_waitcnt lgkmcnt(0)
	v_add_f32_e32 v38, v38, v40
	ds_bpermute_b32 v40, v208, v38
	s_waitcnt lgkmcnt(0)
	v_add_f32_e32 v38, v38, v40
	ds_bpermute_b32 v40, v209, v38
	s_waitcnt lgkmcnt(0)
	v_add_f32_e32 v38, v38, v40
	ds_bpermute_b32 v40, v210, v38
	s_waitcnt lgkmcnt(0)
	v_add_f32_e32 v38, v38, v40
	ds_bpermute_b32 v40, v211, v38
	s_waitcnt lgkmcnt(0)
	v_add_f32_e32 v38, v38, v40
	v_fmamk_f32 v38, v38, 0x3a800000, v217
	v_rsq_f32_e32 v38, v38
	v_mov_b32_e32 v40, v39
	v_pk_mul_f32 v[24:25], v[38:39], v[24:25] op_sel_hi:[0,1]
	v_pk_mul_f32 v[26:27], v[38:39], v[26:27] op_sel_hi:[0,1]
	s_nop 0
	v_mov_b32_e32 v0, v156
	v_mov_b32_e32 v1, v157
	v_mov_b32_e32 v2, v158
	v_mov_b32_e32 v3, v159
	v_pk_mul_f32 v[2:3], v[26:27], v[2:3]
	v_pk_mul_f32 v[0:1], v[24:25], v[0:1]
	v_mov_b32_e32 v24, v32
	v_cvt_pk_bf16_f32 v0, v0, v1
	v_cvt_pk_bf16_f32 v1, v2, v3
	global_store_dwordx2 v[42:43], v[0:1], off
	v_mov_b32_e32 v25, v34
	v_mov_b32_e32 v34, v33
	v_pk_mul_f32 v[24:25], v[38:39], v[24:25] op_sel_hi:[0,1]
	v_pk_mul_f32 v[26:27], v[38:39], v[34:35] op_sel_hi:[0,1]
	s_nop 0
	v_mov_b32_e32 v0, v160
	v_mov_b32_e32 v1, v161
	v_mov_b32_e32 v2, v162
	v_mov_b32_e32 v3, v163
	v_pk_mul_f32 v[2:3], v[26:27], v[2:3]
	v_pk_mul_f32 v[0:1], v[24:25], v[0:1]
	v_pk_mul_f32 v[24:25], v[38:39], v[36:37] op_sel_hi:[0,1]
	v_cvt_pk_bf16_f32 v0, v0, v1
	v_cvt_pk_bf16_f32 v1, v2, v3
	global_store_dwordx2 v[42:43], v[0:1], off offset:512
	v_pk_mul_f32 v[26:27], v[38:39], v[30:31] op_sel_hi:[0,1]
	s_nop 0
	v_mov_b32_e32 v0, v164
	v_mov_b32_e32 v1, v165
	v_mov_b32_e32 v2, v166
	v_mov_b32_e32 v3, v167
	v_pk_mul_f32 v[2:3], v[26:27], v[2:3]
	v_pk_mul_f32 v[0:1], v[24:25], v[0:1]
	v_pk_mul_f32 v[24:25], v[40:41], v[38:39] op_sel_hi:[1,0]
	v_cvt_pk_bf16_f32 v0, v0, v1
	v_cvt_pk_bf16_f32 v1, v2, v3
	global_store_dwordx2 v[42:43], v[0:1], off offset:1024
	v_pk_mul_f32 v[26:27], v[28:29], v[38:39] op_sel_hi:[1,0]
	s_nop 0
	v_mov_b32_e32 v0, v168
	v_mov_b32_e32 v1, v169
	v_mov_b32_e32 v2, v170
	v_mov_b32_e32 v3, v171
	v_pk_mul_f32 v[0:1], v[24:25], v[0:1]
	v_pk_mul_f32 v[2:3], v[26:27], v[2:3]
	v_cvt_pk_bf16_f32 v0, v0, v1
	v_cvt_pk_bf16_f32 v1, v2, v3
	global_store_dwordx2 v[42:43], v[0:1], off offset:1536
	s_branch .LBB0_1586
